# scan waves: y stores addressed with a 32-bit offset against the scalar base (3 VALU instead of 6 with 64-bit ops per store)
# speedup vs baseline: 1.0099x; 1.0022x over previous
; __device__ __forceinline__ bf16_t f2bf(float f) { return (bf16_t)(pk2(f, 0.f) & 0xffffu); }
; __device__ void phase_scan(int l, unsigned char* lds) {
;     ...
;             if ((lane & 15) < jb.nsteps) ybuf[(size_t)(jb.tok0 + (lane & 15)) * 512 + jb.h * 64 + row] = f2bf(yreg0);
;             if (16 + (lane & 15) < jb.nsteps) ybuf[(size_t)(jb.tok0 + 16 + (lane & 15)) * 512 + jb.h * 64 + row] = f2bf(yreg1);
.LBB0_537:
	s_lshl_b32 s9, s51, 4
	s_and_b32 s19, s9, 48
	v_add_u32_e32 v20, s19, v86
	s_and_b32 s64, s9, 0x1c0
	v_ashrrev_i32_e32 v21, 31, v20
	v_cmp_gt_u32_e32 vcc, s8, v106
	s_and_saveexec_b64 s[22:23], vcc
	s_cbranch_execz .LBB0_540
	v_add_u32_e32 v28, s7, v106
	v_add_lshl_u32 v29, v20, s64, 1
	v_lshl_add_u32 v28, v28, 10, v29
	v_cvt_pk_bf16_f32 v18, v18, v19
	global_store_short v28, v18, s[60:61]
	s_or_b64 exec, exec, s[22:23]
	v_cmp_gt_u32_e32 vcc, s8, v107
	s_and_saveexec_b64 s[22:23], vcc
	s_cbranch_execnz .LBB0_541

; __device__ __forceinline__ bf16_t f2bf(float f) { return (bf16_t)(pk2(f, 0.f) & 0xffffu); }
; __device__ void phase_scan(int l, unsigned char* lds) {
;     ...
;             if (16 + (lane & 15) < jb.nsteps) ybuf[(size_t)(jb.tok0 + 16 + (lane & 15)) * 512 + jb.h * 64 + row] = f2bf(yreg1);
.LBB0_541:
	v_add_u32_e32 v28, s7, v107
	v_add_lshl_u32 v29, v20, s64, 1
	v_lshl_add_u32 v28, v28, 10, v29
	v_cvt_pk_bf16_f32 v18, v26, v19
	global_store_short v28, v18, s[60:61]
	s_or_b64 exec, exec, s[22:23]
	s_andn2_b64 vcc, exec, s[20:21]
	s_cbranch_vccnz .LBB0_474

; __device__ __forceinline__ bf16_t f2bf(float f) { return (bf16_t)(pk2(f, 0.f) & 0xffffu); }
; __device__ void phase_scan(int l, unsigned char* lds) {
;     ...
;             if ((lane & 15) < jb.nsteps) ybuf[(size_t)(jb.tok0 + (lane & 15)) * 512 + jb.h * 64 + row] = f2bf(yreg0);
;             if (16 + (lane & 15) < jb.nsteps) ybuf[(size_t)(jb.tok0 + 16 + (lane & 15)) * 512 + jb.h * 64 + row] = f2bf(yreg1);
.LBB0_1678:
	s_lshl_b32 s17, s53, 4
	s_and_b32 s20, s17, 48
	v_add_u32_e32 v20, s20, v86
	s_and_b32 s60, s17, 0x1c0
	v_ashrrev_i32_e32 v21, 31, v20
	v_cmp_gt_u32_e32 vcc, s44, v106
	s_and_saveexec_b64 s[20:21], vcc
	s_cbranch_execz .LBB0_1681
	v_add_u32_e32 v28, s33, v106
	v_add_lshl_u32 v29, v20, s60, 1
	v_lshl_add_u32 v28, v28, 10, v29
	v_cvt_pk_bf16_f32 v18, v18, v19
	global_store_short v28, v18, s[40:41]
	s_or_b64 exec, exec, s[20:21]
	v_cmp_gt_u32_e32 vcc, s44, v107
	s_and_saveexec_b64 s[20:21], vcc
	s_cbranch_execnz .LBB0_1682

; __device__ __forceinline__ bf16_t f2bf(float f) { return (bf16_t)(pk2(f, 0.f) & 0xffffu); }
; __device__ void phase_scan(int l, unsigned char* lds) {
;     ...
;             if (16 + (lane & 15) < jb.nsteps) ybuf[(size_t)(jb.tok0 + 16 + (lane & 15)) * 512 + jb.h * 64 + row] = f2bf(yreg1);
.LBB0_1682:
	v_add_u32_e32 v28, s33, v107
	v_add_lshl_u32 v29, v20, s60, 1
	v_lshl_add_u32 v28, v28, 10, v29
	v_cvt_pk_bf16_f32 v18, v26, v19
	global_store_short v28, v18, s[40:41]
	s_or_b64 exec, exec, s[20:21]
	s_andn2_b64 vcc, exec, s[18:19]
	s_cbranch_vccnz .LBB0_1615
